# flash queue order inside a per-XCD queue: 256-row blocks 7,6,5,2,1,0 then 4,3 (one of the last 256 units per workgroup when the sample-attention workgroups join)
# baseline (speedup 1.0000x reference)
.Lfq_got:
	s_lshr_b32 s92, s10, 4
	s_lshl_b32 s92, s92, 2
	s_lshr_b32 s92, 0x43765210, s92
	s_and_b32 s92, s92, 7
	s_lshl_b32 s92, s92, 7
	s_bfe_u32 s93, s10, 0x20002
	s_lshl_b32 s97, s97, 2
	s_add_i32 s93, s93, s97
	s_lshl_b32 s93, s93, 2
	s_and_b32 s10, s10, 3
	s_or_b32 s10, s10, s93
	s_or_b32 s10, s10, s92
	s_branch .Lfq_done
